# re-balance: pooling/kv items 0..1151 on workgroups 64..255, 1152..2147 on all; left-over in-proj tile last on workgroups 0..63
# speedup vs baseline: 1.0269x; 1.0059x over previous
; __device__ __forceinline__ void run_phase(const Params& p, int ph, LAS unsigned char* lds, const int tid, const int bid) {
;     ...
;     } else if (sub == 1) { if (PH_MASK & 4)
;         for (int it = bid; it < 1024 + 544 + 580; it += G) {
;             if (it < 1024) sample_ret_unit(p, l, it, lds, tid);
;             else if (it < 1568) kv_unit(p, it - 1024, lds, tid);
;             else pool_item(p, l, it - 1568, tid);
;         }
.LBB0_447:
	s_andn2_b64 vcc, exec, s[0:1]
	s_cbranch_vccnz .LBB0_582
	v_readlane_b32 s0, v254, 48
	s_and_b32 s0, 0xffff, s0
	s_cmp_gt_i32 s0, 0
	s_mov_b64 s[0:1], -1
	s_cbranch_scc0 .LBB0_547
	s_cmpk_gt_i32 s82, 0x863
	s_cbranch_scc1 .LBB0_546
	v_readlane_b32 s0, v254, 46
	v_readlane_b32 s1, v254, 47
	s_mov_b32 s1, s91
	v_readlane_b32 s8, v253, 57
	s_lshl_b64 s[22:23], s[0:1], 7
	s_lshl_b64 s[24:25], s[0:1], 2
	s_lshl_b64 s[26:27], s[0:1], 10
	s_mov_b32 s6, s0
	s_lshl_b64 s[0:1], s[0:1], 13
	v_readlane_b32 s10, v253, 59
	v_readlane_b32 s11, v253, 60
	s_add_u32 s34, s10, s0
	v_writelane_b32 v254, s6, 46
	s_addc_u32 s35, s11, s1
	s_mov_b32 s38, s82
	s_cmpk_lg_u32 s42, 0x100
	s_cbranch_scc1 .Lp2_fwd0
	s_bitcmp1_b32 s82, 3
	s_cbranch_scc1 .Lz2_ibwd
	s_mov_b32 s0, 0
	s_add_i32 s38, s82, 0xffffffc0
	s_cmpk_gt_u32 s82, 63
	s_cbranch_scc1 .Lz2_iset
	s_mov_b32 s0, 1
	s_add_i32 s38, s82, 0x480
	s_branch .Lz2_iset
.Lz2_ibwd:
	s_mov_b32 s0, 1
	s_sub_i32 s38, 0x3e3, s82
	s_andn2_b32 s38, s38, 0xff
	s_add_i32 s38, s38, s82
	s_add_i32 s38, s38, 0x480

; __device__ __forceinline__ void run_phase(const Params& p, int ph, LAS unsigned char* lds, const int tid, const int bid) {
;     ...
;         for (int it = bid; it < 1024 + 544 + 580; it += G) {
;             if (it < 1024) sample_ret_unit(p, l, it, lds, tid);
;             else if (it < 1568) kv_unit(p, it - 1024, lds, tid);
;             else pool_item(p, l, it - 1568, tid);
;         }
.LBB0_451:
	s_cmpk_lg_u32 s42, 0x100
	s_cbranch_scc1 .Lz2_generic
	v_readlane_b32 s1, v255, 9
	s_bitcmp1_b32 s82, 3
	s_cbranch_scc1 .Lz2_lbwd
	s_cmp_eq_u32 s1, 0
	s_cbranch_scc0 .Lz2_fB
	s_addk_i32 s38, 0xc0
	s_cmpk_lt_i32 s38, 0x480
	s_cbranch_scc1 .Lz2_lset
	s_mov_b32 s1, 1
	s_nop 0
	v_writelane_b32 v255, s1, 9
	s_add_i32 s38, s82, 0x480
	s_branch .Lz2_lset

; __device__ __forceinline__ void run_phase(const Params& p, int ph, LAS unsigned char* lds, const int tid, const int bid) {
;     ...
;         for (int it = bid; it < 1024 + 544 + 580; it += G) {
;             if (it < 1024) sample_ret_unit(p, l, it, lds, tid);
;             else if (it < 1568) kv_unit(p, it - 1024, lds, tid);
;             else pool_item(p, l, it - 1568, tid);
;         }
.Lz2_lbwd:
	s_cmp_eq_u32 s1, 0
	s_cbranch_scc1 .Lz2_bA
	s_addk_i32 s38, 0xff00
	s_cmpk_ge_i32 s38, 0x480
	s_cbranch_scc1 .Lz2_lset
	s_cmpk_lt_u32 s82, 64
	s_cbranch_scc1 .LBB0_546
	s_mov_b32 s1, 0
	s_nop 0
	v_writelane_b32 v255, s1, 9
	s_add_i32 s38, s82, 0x380
	s_branch .Lz2_lset
